# one static s_setprio 1 at kernel entry for waves 4-7 (the trailing half of every GEMM K-loop); no per-segment priority flips
# speedup vs baseline: 1.0024x; 1.0024x over previous
; #define LAS __attribute__((address_space(3)))
; #define KARG ((const __attribute__((address_space(4))) Args*)__builtin_amdgcn_kernarg_segment_ptr())
; #define STAMP(i) do { if (F.bid == PROBE_BID && F.tid == 0 && ((i) == PROBE_A || (i) == PROBE_B)) { const unsigned long long t_ = __builtin_amdgcn_s_memrealtime(); volatile LAS unsigned* m_ = (volatile LAS unsigned*)(F.lds + MISC_OFF) + ((i) == PROBE_A ? 16 : 18); m_[0] = (unsigned)t_; m_[1] = (unsigned)(t_ >> 32); } } while (0)
; #define STAMP(i) do { } while (0)
; #define SEAM(k) do { if (IN(k) && IN((k) + 1)) { XcdBarrier b_; b_.bar = (unsigned*)(P_ctl + CW_BAR); b_.x = xb_xcc_id(); b_.st = MISC + 8; xcd_barrier(b_); } } while (0)
; __global__ void __launch_bounds__(NWAVES * 64, 2) hymba_fwd(Args args) {
;     ...
;     Frame F; F.lds = (LAS unsigned char*)lds_raw; F.tid = threadIdx.x; F.lane = F.tid & 63; F.wave = __builtin_amdgcn_readfirstlane(F.tid >> 6); F.G = KARG->grid; F.bid = blockIdx.x;
;     volatile LAS unsigned* MISC = (volatile LAS unsigned*)(F.lds + MISC_OFF);
;     Ptrs P;
;     for (int u = F.tid; u < (LDS_BYTES - LDSCTL_OFF) / 4; u += NWAVES * 64) ((LAS unsigned*)(F.lds + LDSCTL_OFF))[u] = 0u;
;     __syncthreads();
;     if (N_LAUNCHES == 1) (void)xcd_barrier_post((unsigned*)(P_ctl + CW_BAR), MISC + 8);
;     const int lo = KARG->ph_lo, hi = KARG->ph_hi;
;     STAMP(0);
;     ...
;     if (IN(0)) { for (int rep = 0; rep < NREP_P0; ++rep) p0_prologue(F, P); } SEAM(0); STAMP(1);
.LBB0_5:
	s_or_b64 exec, exec, s[4:5]
	s_load_dwordx2 s[6:7], s[0:1], 0xe0
	s_lshr_b32 s94, s60, 6
	s_cmp_lt_u32 s94, 4
	s_cbranch_scc1 .Lprio_skip
	s_setprio 1
.Lprio_skip:
	v_and_b32_e32 v189, 63, v0
	s_waitcnt lgkmcnt(0)
	s_cmp_lt_i32 s6, 1
	s_cselect_b64 s[4:5], -1, 0
	s_cmp_gt_i32 s7, 0
	s_cselect_b64 s[6:7], -1, 0
	s_and_b64 s[6:7], s[4:5], s[6:7]
	s_andn2_b64 vcc, exec, s[6:7]
	s_cbranch_vccnz .LBB0_20
